# attention: idle map-1 waves prefetch the next unit's Q and diagonal K/V tile lines into L2 during the unit epilogue
# speedup vs baseline: 1.0067x; 1.0067x over previous
.LBB0_559:
	s_andn2_b64 vcc, exec, s[10:11]
	s_cbranch_vccnz .Lmy_epi_noload
	s_and_saveexec_b64 s[98:99], s[26:27]
	s_waitcnt vmcnt(0)
	v_mov_b32_e32 v244, 0x22830
	ds_write_b32 v244, v218
	s_or_b64 exec, exec, s[98:99]
	v_lshlrev_b64 v[240:241], 11, v[182:183]
	s_lshl_b32 s4, s78, 8
	v_and_b32_e32 v242, 32, v1
	v_mov_b32_e32 v243, 0
	v_lshrrev_b32_e32 v242, 2, v242
	v_or_b32_e32 v240, s4, v240
	v_lshl_add_u64 v[240:241], v[174:175], 0, v[240:241]
	v_lshl_add_u64 v[240:241], v[240:241], 0, v[242:243]
	global_load_dwordx4 v[152:155], v[240:241], off offset:0
	global_load_dwordx4 v[156:159], v[240:241], off offset:32
	global_load_dwordx4 v[160:163], v[240:241], off offset:64
	global_load_dwordx4 v[220:223], v[240:241], off offset:96
	global_load_dwordx4 v[224:227], v[240:241], off offset:128
	global_load_dwordx4 v[228:231], v[240:241], off offset:160
	global_load_dwordx4 v[232:235], v[240:241], off offset:192
	global_load_dwordx4 v[236:239], v[240:241], off offset:224

.LBB0_563:
	s_andn2_b64 vcc, exec, s[12:13]
	s_cbranch_vccnz .Lmy_pf_skip
	v_mov_b32_e32 v240, 0x22830
	ds_read_b32 v240, v240
	s_waitcnt lgkmcnt(0)
	v_readfirstlane_b32 s98, v240
	s_nop 3
	s_cmp_gt_u32 s98, 0x7ff
	s_cbranch_scc1 .Lmy_pf_skip
	s_and_b32 s4, s98, 0xffffff80
	s_sub_i32 s4, 0x780, s4
	s_lshl_b32 s5, s98, 8
	s_and_b32 s5, s5, 0x7800
	s_add_i32 s4, s4, s5
	s_and_b32 s5, s98, 7
	s_lshl_b32 s5, s5, 8
	v_lshrrev_b32_e32 v240, 1, v1
	v_and_b32_e32 v240, 0xc0, v240
	v_and_b32_e32 v241, 63, v1
	v_or_b32_e32 v240, v240, v241
	v_lshrrev_b32_e32 v241, 1, v240
	v_add_u32_e32 v241, s4, v241
	v_and_b32_e32 v240, 1, v240
	v_lshlrev_b32_e32 v240, 7, v240
	v_lshlrev_b32_e32 v241, 11, v241
	v_add3_u32 v240, v241, v240, s5
	v_mov_b32_e32 v241, 0
	v_lshl_add_u64 v[242:243], s[38:39], 0, v[240:241]
	global_load_dword v250, v[242:243], off
	v_mov_b32_e32 v243, s64
	v_add_co_u32_e32 v242, vcc, s63, v240
	s_nop 1
	v_addc_co_u32_e32 v243, vcc, 0, v243, vcc
	global_load_dword v250, v[242:243], off
	v_mov_b32_e32 v245, s70
	v_add_co_u32_e32 v244, vcc, s65, v240
	s_nop 1
	v_addc_co_u32_e32 v245, vcc, 0, v245, vcc
	global_load_dword v250, v[244:245], off
